# v80 + s_sleep 1 back-off after a failed MLA progress-flag poll (a wave that is ahead stops stealing issue slots from its SIMD partner)
# baseline (speedup 1.0000x reference)
; DI void phase_attn_mla(const Params& P, bf16_t* og, unsigned char* smem, int L, int G) {
;     ...
;     for (int j = 0; j <= jhi; ++j) {
;       const int key0 = j * 64, cb = j & 1;
;       __syncthreads();
.Lmy_mla_spin:
	ds_read_b32 v251, v250
	s_waitcnt lgkmcnt(0)
	v_cmp_gt_u32_e32 vcc, s26, v251
	s_cbranch_vccz .Lmy_mla_go
	s_sleep 1
	s_add_i32 s99, s99, 1
	s_cmp_lt_u32 s99, 0x40000
	s_cbranch_scc1 .Lmy_mla_spin
